# phase-0 S5 kernel table: 64-term sum unrolled with the loads of four trips ahead in flight (hipcc's per-trip arithmetic verbatim)
# baseline (speedup 1.0000x reference)
; __device__ __forceinline__ void phase0a(const int wvs, const Params& p, LAS unsigned char* lds) {
;     ...
;       if (tid < 256) { const int c = tid >> 4, cp = tid & 15; float s = 0.f;
;         const float* cre = p.in[I_CRE] + ((size_t)(l * 16 + g) * 16 + c) * 64; const float* cim = p.in[I_CIM] + ((size_t)(l * 16 + g) * 16 + c) * 64;
;         const float* bre = p.in[I_BRE] + ((size_t)(l * 16 + g) * 64) * 16 + cp; const float* bim = p.in[I_BIM] + ((size_t)(l * 16 + g) * 64) * 16 + cp;
;         for (int q = 0; q < 64; ++q) { const float tr = T[q * 2], ti = T[q * 2 + 1], xr = cre[q], xi = cim[q], yr = bre[q * 16], yi = bim[q * 16];
;           const float ur = xr * tr - xi * ti, ui = xr * ti + xi * tr; s += ur * yr - ui * yi; }
;         kd[(((size_t)(l * 2 + d) * 16 + g) * 16 + delta) * 256 + tid] = s; }
.LBB0_23:
	s_or_b64 exec, exec, s[26:27]
	s_waitcnt lgkmcnt(0)
	s_barrier
	s_and_saveexec_b64 s[6:7], s[4:5]
	s_cbranch_execz .LBB0_12
	s_lshl_b32 s8, s25, 4
	s_add_i32 s8, s8, s24
	s_ashr_i32 s9, s8, 31
	s_lshl_b64 s[8:9], s[8:9], 12
	v_mov_b32_e32 v6, 0
	s_mov_b32 s10, 0
	v_mov_b64_e32 v[16:17], v[10:11]
	v_mov_b64_e32 v[18:19], v[8:9]
	v_mov_b64_e32 v[20:21], v[14:15]
	v_mov_b64_e32 v[22:23], v[12:13]
	v_lshl_add_u64 v[92:93], v[22:23], 0, s[8:9]
	v_lshl_add_u64 v[94:95], v[20:21], 0, s[8:9]
	v_lshl_add_u64 v[96:97], v[18:19], 0, s[8:9]
	v_lshl_add_u64 v[98:99], v[16:17], 0, s[8:9]
	global_load_dwordx4 v[100:103], v[92:93], off
	global_load_dwordx4 v[104:107], v[94:95], off
	global_load_dword v109, v[98:99], off
	global_load_dword v111, v[98:99], off offset:64
	global_load_dword v113, v[98:99], off offset:128
	global_load_dword v108, v[96:97], off
	global_load_dword v110, v[96:97], off offset:64
	global_load_dword v112, v[96:97], off offset:128
	global_load_dword v114, v[96:97], off offset:192
	global_load_dword v115, v[98:99], off offset:192
	v_lshl_add_u64 v[22:23], v[22:23], 0, 16
	v_lshl_add_u64 v[20:21], v[20:21], 0, 16
	v_lshl_add_u64 v[18:19], v[18:19], 0, s[20:21]
	v_lshl_add_u64 v[16:17], v[16:17], 0, s[20:21]
	v_lshl_add_u64 v[92:93], v[22:23], 0, s[8:9]
	v_lshl_add_u64 v[94:95], v[20:21], 0, s[8:9]
	v_lshl_add_u64 v[96:97], v[18:19], 0, s[8:9]
	v_lshl_add_u64 v[98:99], v[16:17], 0, s[8:9]
	global_load_dwordx4 v[116:119], v[92:93], off
	global_load_dwordx4 v[120:123], v[94:95], off
	global_load_dword v125, v[98:99], off
	global_load_dword v127, v[98:99], off offset:64
	global_load_dword v129, v[98:99], off offset:128
	global_load_dword v124, v[96:97], off
	global_load_dword v126, v[96:97], off offset:64
	global_load_dword v128, v[96:97], off offset:128
	global_load_dword v130, v[96:97], off offset:192
	global_load_dword v131, v[98:99], off offset:192
	v_lshl_add_u64 v[22:23], v[22:23], 0, 16
	v_lshl_add_u64 v[20:21], v[20:21], 0, 16
	v_lshl_add_u64 v[18:19], v[18:19], 0, s[20:21]
	v_lshl_add_u64 v[16:17], v[16:17], 0, s[20:21]
	v_lshl_add_u64 v[92:93], v[22:23], 0, s[8:9]
	v_lshl_add_u64 v[94:95], v[20:21], 0, s[8:9]
	v_lshl_add_u64 v[96:97], v[18:19], 0, s[8:9]
	v_lshl_add_u64 v[98:99], v[16:17], 0, s[8:9]
	global_load_dwordx4 v[132:135], v[92:93], off
	global_load_dwordx4 v[136:139], v[94:95], off
	global_load_dword v141, v[98:99], off
	global_load_dword v143, v[98:99], off offset:64
	global_load_dword v145, v[98:99], off offset:128
	global_load_dword v140, v[96:97], off
	global_load_dword v142, v[96:97], off offset:64
	global_load_dword v144, v[96:97], off offset:128
	global_load_dword v146, v[96:97], off offset:192
	global_load_dword v147, v[98:99], off offset:192
	v_lshl_add_u64 v[22:23], v[22:23], 0, 16
	v_lshl_add_u64 v[20:21], v[20:21], 0, 16
	v_lshl_add_u64 v[18:19], v[18:19], 0, s[20:21]
	v_lshl_add_u64 v[16:17], v[16:17], 0, s[20:21]
	v_lshl_add_u64 v[92:93], v[22:23], 0, s[8:9]
	v_lshl_add_u64 v[94:95], v[20:21], 0, s[8:9]
	v_lshl_add_u64 v[96:97], v[18:19], 0, s[8:9]
	v_lshl_add_u64 v[98:99], v[16:17], 0, s[8:9]
	global_load_dwordx4 v[148:151], v[92:93], off
	global_load_dwordx4 v[152:155], v[94:95], off
	global_load_dword v157, v[98:99], off
	global_load_dword v159, v[98:99], off offset:64
	global_load_dword v161, v[98:99], off offset:128
	global_load_dword v156, v[96:97], off
	global_load_dword v158, v[96:97], off offset:64
	global_load_dword v160, v[96:97], off offset:128
	global_load_dword v162, v[96:97], off offset:192
	global_load_dword v163, v[98:99], off offset:192
	v_lshl_add_u64 v[22:23], v[22:23], 0, 16
	v_lshl_add_u64 v[20:21], v[20:21], 0, 16
	v_lshl_add_u64 v[18:19], v[18:19], 0, s[20:21]
	v_lshl_add_u64 v[16:17], v[16:17], 0, s[20:21]
	s_waitcnt vmcnt(30)
	v_mov_b64_e32 v[32:33], v[100:101]
	v_mov_b64_e32 v[34:35], v[102:103]
	v_mov_b64_e32 v[36:37], v[104:105]
	v_mov_b64_e32 v[38:39], v[106:107]
	v_mov_b64_e32 v[48:49], v[108:109]
	v_mov_b64_e32 v[50:51], v[110:111]
	v_mov_b64_e32 v[52:53], v[112:113]
	v_mov_b64_e32 v[54:55], v[114:115]
	s_add_i32 s11, s10, 0
	v_mov_b32_e32 v31, s11
	ds_read_b128 v[40:43], v31
	ds_read_b128 v[44:47], v31 offset:16
	s_add_i32 s10, s10, 32
	s_waitcnt lgkmcnt(1)
	v_pk_mul_f32 v[56:57], v[40:41], v[32:33] op_sel:[1,0] op_sel_hi:[0,0]
	v_mov_b32_e32 v58, v37
	v_pk_mul_f32 v[32:33], v[42:43], v[32:33] op_sel:[1,1] op_sel_hi:[0,1]
	s_waitcnt lgkmcnt(0)
	v_pk_mul_f32 v[60:61], v[44:45], v[34:35] op_sel:[1,0] op_sel_hi:[0,0]
	v_pk_fma_f32 v[66:67], v[40:41], v[36:37], v[56:57] neg_lo:[0,0,1] neg_hi:[0,0,1]
	v_pk_fma_f32 v[40:41], v[40:41], v[36:37], v[56:57] op_sel_hi:[1,0,1]
	v_mov_b32_e32 v34, v39
	v_mov_b32_e32 v62, v39
	v_mov_b32_e32 v64, v35
	v_pk_fma_f32 v[56:57], v[42:43], v[58:59], v[32:33] neg_lo:[0,0,1] neg_hi:[0,0,1]
	v_pk_fma_f32 v[32:33], v[42:43], v[36:37], v[32:33] op_sel:[0,1,0]
	v_pk_fma_f32 v[36:37], v[44:45], v[38:39], v[60:61] neg_lo:[0,0,1] neg_hi:[0,0,1]
	v_pk_fma_f32 v[38:39], v[44:45], v[38:39], v[60:61] op_sel_hi:[1,0,1]
	v_mov_b32_e32 v67, v41
	v_pk_mul_f32 v[42:43], v[46:47], v[64:65] op_sel:[1,0] op_sel_hi:[0,0]
	v_mov_b32_e32 v57, v33
	v_mov_b32_e32 v37, v39
	v_pk_mul_f32 v[38:39], v[48:49], v[66:67]
	v_pk_fma_f32 v[32:33], v[46:47], v[34:35], v[42:43] neg_lo:[0,0,1] neg_hi:[0,0,1]
	v_pk_fma_f32 v[34:35], v[46:47], v[62:63], v[42:43] op_sel_hi:[1,0,1]
	v_pk_mul_f32 v[40:41], v[50:51], v[56:57]
	v_sub_f32_e32 v31, v38, v39
	v_pk_mul_f32 v[36:37], v[52:53], v[36:37]
	v_mov_b32_e32 v33, v35
	v_sub_f32_e32 v34, v40, v41
	v_add_f32_e32 v6, v6, v31
	v_sub_f32_e32 v35, v36, v37
	v_pk_mul_f32 v[32:33], v[54:55], v[32:33]
	v_add_f32_e32 v6, v6, v34
	v_sub_f32_e32 v31, v32, v33
	v_add_f32_e32 v6, v6, v35
	v_add_f32_e32 v6, v6, v31
	v_lshl_add_u64 v[92:93], v[22:23], 0, s[8:9]
	v_lshl_add_u64 v[94:95], v[20:21], 0, s[8:9]
	v_lshl_add_u64 v[96:97], v[18:19], 0, s[8:9]
	v_lshl_add_u64 v[98:99], v[16:17], 0, s[8:9]
	global_load_dwordx4 v[100:103], v[92:93], off
	global_load_dwordx4 v[104:107], v[94:95], off
	global_load_dword v109, v[98:99], off
	global_load_dword v111, v[98:99], off offset:64
	global_load_dword v113, v[98:99], off offset:128
	global_load_dword v108, v[96:97], off
	global_load_dword v110, v[96:97], off offset:64
	global_load_dword v112, v[96:97], off offset:128
	global_load_dword v114, v[96:97], off offset:192
	global_load_dword v115, v[98:99], off offset:192
	v_lshl_add_u64 v[22:23], v[22:23], 0, 16
	v_lshl_add_u64 v[20:21], v[20:21], 0, 16
	v_lshl_add_u64 v[18:19], v[18:19], 0, s[20:21]
	v_lshl_add_u64 v[16:17], v[16:17], 0, s[20:21]
	s_waitcnt vmcnt(30)
; __device__ __forceinline__ void phase0a(const int wvs, const Params& p, LAS unsigned char* lds) {
;     ...
;       if (tid < 256) { const int c = tid >> 4, cp = tid & 15; float s = 0.f;
;         const float* cre = p.in[I_CRE] + ((size_t)(l * 16 + g) * 16 + c) * 64; const float* cim = p.in[I_CIM] + ((size_t)(l * 16 + g) * 16 + c) * 64;
;         const float* bre = p.in[I_BRE] + ((size_t)(l * 16 + g) * 64) * 16 + cp; const float* bim = p.in[I_BIM] + ((size_t)(l * 16 + g) * 64) * 16 + cp;
;         for (int q = 0; q < 64; ++q) { const float tr = T[q * 2], ti = T[q * 2 + 1], xr = cre[q], xi = cim[q], yr = bre[q * 16], yi = bim[q * 16];
;           const float ur = xr * tr - xi * ti, ui = xr * ti + xi * tr; s += ur * yr - ui * yi; }
;         kd[(((size_t)(l * 2 + d) * 16 + g) * 16 + delta) * 256 + tid] = s; }
	v_mov_b64_e32 v[32:33], v[116:117]
	v_mov_b64_e32 v[34:35], v[118:119]
	v_mov_b64_e32 v[36:37], v[120:121]
	v_mov_b64_e32 v[38:39], v[122:123]
	v_mov_b64_e32 v[48:49], v[124:125]
	v_mov_b64_e32 v[50:51], v[126:127]
	v_mov_b64_e32 v[52:53], v[128:129]
	v_mov_b64_e32 v[54:55], v[130:131]
	s_add_i32 s11, s10, 0
	v_mov_b32_e32 v31, s11
	ds_read_b128 v[40:43], v31
	ds_read_b128 v[44:47], v31 offset:16
	s_add_i32 s10, s10, 32
	s_waitcnt lgkmcnt(1)
	v_pk_mul_f32 v[56:57], v[40:41], v[32:33] op_sel:[1,0] op_sel_hi:[0,0]
	v_mov_b32_e32 v58, v37
	v_pk_mul_f32 v[32:33], v[42:43], v[32:33] op_sel:[1,1] op_sel_hi:[0,1]
	s_waitcnt lgkmcnt(0)
	v_pk_mul_f32 v[60:61], v[44:45], v[34:35] op_sel:[1,0] op_sel_hi:[0,0]
	v_pk_fma_f32 v[66:67], v[40:41], v[36:37], v[56:57] neg_lo:[0,0,1] neg_hi:[0,0,1]
	v_pk_fma_f32 v[40:41], v[40:41], v[36:37], v[56:57] op_sel_hi:[1,0,1]
	v_mov_b32_e32 v34, v39
	v_mov_b32_e32 v62, v39
	v_mov_b32_e32 v64, v35
	v_pk_fma_f32 v[56:57], v[42:43], v[58:59], v[32:33] neg_lo:[0,0,1] neg_hi:[0,0,1]
	v_pk_fma_f32 v[32:33], v[42:43], v[36:37], v[32:33] op_sel:[0,1,0]
	v_pk_fma_f32 v[36:37], v[44:45], v[38:39], v[60:61] neg_lo:[0,0,1] neg_hi:[0,0,1]
	v_pk_fma_f32 v[38:39], v[44:45], v[38:39], v[60:61] op_sel_hi:[1,0,1]
	v_mov_b32_e32 v67, v41
	v_pk_mul_f32 v[42:43], v[46:47], v[64:65] op_sel:[1,0] op_sel_hi:[0,0]
	v_mov_b32_e32 v57, v33
	v_mov_b32_e32 v37, v39
	v_pk_mul_f32 v[38:39], v[48:49], v[66:67]
	v_pk_fma_f32 v[32:33], v[46:47], v[34:35], v[42:43] neg_lo:[0,0,1] neg_hi:[0,0,1]
	v_pk_fma_f32 v[34:35], v[46:47], v[62:63], v[42:43] op_sel_hi:[1,0,1]
	v_pk_mul_f32 v[40:41], v[50:51], v[56:57]
	v_sub_f32_e32 v31, v38, v39
	v_pk_mul_f32 v[36:37], v[52:53], v[36:37]
	v_mov_b32_e32 v33, v35
	v_sub_f32_e32 v34, v40, v41
	v_add_f32_e32 v6, v6, v31
	v_sub_f32_e32 v35, v36, v37
	v_pk_mul_f32 v[32:33], v[54:55], v[32:33]
	v_add_f32_e32 v6, v6, v34
	v_sub_f32_e32 v31, v32, v33
	v_add_f32_e32 v6, v6, v35
	v_add_f32_e32 v6, v6, v31
	v_lshl_add_u64 v[92:93], v[22:23], 0, s[8:9]
	v_lshl_add_u64 v[94:95], v[20:21], 0, s[8:9]
	v_lshl_add_u64 v[96:97], v[18:19], 0, s[8:9]
	v_lshl_add_u64 v[98:99], v[16:17], 0, s[8:9]
	global_load_dwordx4 v[116:119], v[92:93], off
	global_load_dwordx4 v[120:123], v[94:95], off
	global_load_dword v125, v[98:99], off
	global_load_dword v127, v[98:99], off offset:64
	global_load_dword v129, v[98:99], off offset:128
	global_load_dword v124, v[96:97], off
	global_load_dword v126, v[96:97], off offset:64
	global_load_dword v128, v[96:97], off offset:128
	global_load_dword v130, v[96:97], off offset:192
	global_load_dword v131, v[98:99], off offset:192
	v_lshl_add_u64 v[22:23], v[22:23], 0, 16
	v_lshl_add_u64 v[20:21], v[20:21], 0, 16
	v_lshl_add_u64 v[18:19], v[18:19], 0, s[20:21]
	v_lshl_add_u64 v[16:17], v[16:17], 0, s[20:21]
	s_waitcnt vmcnt(30)
	v_mov_b64_e32 v[32:33], v[132:133]
	v_mov_b64_e32 v[34:35], v[134:135]
	v_mov_b64_e32 v[36:37], v[136:137]
	v_mov_b64_e32 v[38:39], v[138:139]
	v_mov_b64_e32 v[48:49], v[140:141]
	v_mov_b64_e32 v[50:51], v[142:143]
	v_mov_b64_e32 v[52:53], v[144:145]
	v_mov_b64_e32 v[54:55], v[146:147]
	s_add_i32 s11, s10, 0
	v_mov_b32_e32 v31, s11
	ds_read_b128 v[40:43], v31
	ds_read_b128 v[44:47], v31 offset:16
	s_add_i32 s10, s10, 32
	s_waitcnt lgkmcnt(1)
	v_pk_mul_f32 v[56:57], v[40:41], v[32:33] op_sel:[1,0] op_sel_hi:[0,0]
	v_mov_b32_e32 v58, v37
	v_pk_mul_f32 v[32:33], v[42:43], v[32:33] op_sel:[1,1] op_sel_hi:[0,1]
	s_waitcnt lgkmcnt(0)
	v_pk_mul_f32 v[60:61], v[44:45], v[34:35] op_sel:[1,0] op_sel_hi:[0,0]
	v_pk_fma_f32 v[66:67], v[40:41], v[36:37], v[56:57] neg_lo:[0,0,1] neg_hi:[0,0,1]
	v_pk_fma_f32 v[40:41], v[40:41], v[36:37], v[56:57] op_sel_hi:[1,0,1]
	v_mov_b32_e32 v34, v39
	v_mov_b32_e32 v62, v39
	v_mov_b32_e32 v64, v35
	v_pk_fma_f32 v[56:57], v[42:43], v[58:59], v[32:33] neg_lo:[0,0,1] neg_hi:[0,0,1]
	v_pk_fma_f32 v[32:33], v[42:43], v[36:37], v[32:33] op_sel:[0,1,0]
	v_pk_fma_f32 v[36:37], v[44:45], v[38:39], v[60:61] neg_lo:[0,0,1] neg_hi:[0,0,1]
	v_pk_fma_f32 v[38:39], v[44:45], v[38:39], v[60:61] op_sel_hi:[1,0,1]
	v_mov_b32_e32 v67, v41
	v_pk_mul_f32 v[42:43], v[46:47], v[64:65] op_sel:[1,0] op_sel_hi:[0,0]
	v_mov_b32_e32 v57, v33
	v_mov_b32_e32 v37, v39
	v_pk_mul_f32 v[38:39], v[48:49], v[66:67]
	v_pk_fma_f32 v[32:33], v[46:47], v[34:35], v[42:43] neg_lo:[0,0,1] neg_hi:[0,0,1]
	v_pk_fma_f32 v[34:35], v[46:47], v[62:63], v[42:43] op_sel_hi:[1,0,1]
	v_pk_mul_f32 v[40:41], v[50:51], v[56:57]
	v_sub_f32_e32 v31, v38, v39
	v_pk_mul_f32 v[36:37], v[52:53], v[36:37]
	v_mov_b32_e32 v33, v35
	v_sub_f32_e32 v34, v40, v41
	v_add_f32_e32 v6, v6, v31
	v_sub_f32_e32 v35, v36, v37
	v_pk_mul_f32 v[32:33], v[54:55], v[32:33]
	v_add_f32_e32 v6, v6, v34
	v_sub_f32_e32 v31, v32, v33
	v_add_f32_e32 v6, v6, v35
	v_add_f32_e32 v6, v6, v31
	v_lshl_add_u64 v[92:93], v[22:23], 0, s[8:9]
	v_lshl_add_u64 v[94:95], v[20:21], 0, s[8:9]
	v_lshl_add_u64 v[96:97], v[18:19], 0, s[8:9]
	v_lshl_add_u64 v[98:99], v[16:17], 0, s[8:9]
	global_load_dwordx4 v[132:135], v[92:93], off
	global_load_dwordx4 v[136:139], v[94:95], off
	global_load_dword v141, v[98:99], off
	global_load_dword v143, v[98:99], off offset:64
	global_load_dword v145, v[98:99], off offset:128
	global_load_dword v140, v[96:97], off
	global_load_dword v142, v[96:97], off offset:64
	global_load_dword v144, v[96:97], off offset:128
	global_load_dword v146, v[96:97], off offset:192
	global_load_dword v147, v[98:99], off offset:192
	v_lshl_add_u64 v[22:23], v[22:23], 0, 16
	v_lshl_add_u64 v[20:21], v[20:21], 0, 16
	v_lshl_add_u64 v[18:19], v[18:19], 0, s[20:21]
	v_lshl_add_u64 v[16:17], v[16:17], 0, s[20:21]
	s_waitcnt vmcnt(30)
; __device__ __forceinline__ void phase0a(const int wvs, const Params& p, LAS unsigned char* lds) {
;     ...
;       if (tid < 256) { const int c = tid >> 4, cp = tid & 15; float s = 0.f;
;         const float* cre = p.in[I_CRE] + ((size_t)(l * 16 + g) * 16 + c) * 64; const float* cim = p.in[I_CIM] + ((size_t)(l * 16 + g) * 16 + c) * 64;
;         const float* bre = p.in[I_BRE] + ((size_t)(l * 16 + g) * 64) * 16 + cp; const float* bim = p.in[I_BIM] + ((size_t)(l * 16 + g) * 64) * 16 + cp;
;         for (int q = 0; q < 64; ++q) { const float tr = T[q * 2], ti = T[q * 2 + 1], xr = cre[q], xi = cim[q], yr = bre[q * 16], yi = bim[q * 16];
;           const float ur = xr * tr - xi * ti, ui = xr * ti + xi * tr; s += ur * yr - ui * yi; }
;         kd[(((size_t)(l * 2 + d) * 16 + g) * 16 + delta) * 256 + tid] = s; }
	v_mov_b64_e32 v[32:33], v[148:149]
	v_mov_b64_e32 v[34:35], v[150:151]
	v_mov_b64_e32 v[36:37], v[152:153]
	v_mov_b64_e32 v[38:39], v[154:155]
	v_mov_b64_e32 v[48:49], v[156:157]
	v_mov_b64_e32 v[50:51], v[158:159]
	v_mov_b64_e32 v[52:53], v[160:161]
	v_mov_b64_e32 v[54:55], v[162:163]
	s_add_i32 s11, s10, 0
	v_mov_b32_e32 v31, s11
	ds_read_b128 v[40:43], v31
	ds_read_b128 v[44:47], v31 offset:16
	s_add_i32 s10, s10, 32
	s_waitcnt lgkmcnt(1)
	v_pk_mul_f32 v[56:57], v[40:41], v[32:33] op_sel:[1,0] op_sel_hi:[0,0]
	v_mov_b32_e32 v58, v37
	v_pk_mul_f32 v[32:33], v[42:43], v[32:33] op_sel:[1,1] op_sel_hi:[0,1]
	s_waitcnt lgkmcnt(0)
	v_pk_mul_f32 v[60:61], v[44:45], v[34:35] op_sel:[1,0] op_sel_hi:[0,0]
	v_pk_fma_f32 v[66:67], v[40:41], v[36:37], v[56:57] neg_lo:[0,0,1] neg_hi:[0,0,1]
	v_pk_fma_f32 v[40:41], v[40:41], v[36:37], v[56:57] op_sel_hi:[1,0,1]
	v_mov_b32_e32 v34, v39
	v_mov_b32_e32 v62, v39
	v_mov_b32_e32 v64, v35
	v_pk_fma_f32 v[56:57], v[42:43], v[58:59], v[32:33] neg_lo:[0,0,1] neg_hi:[0,0,1]
	v_pk_fma_f32 v[32:33], v[42:43], v[36:37], v[32:33] op_sel:[0,1,0]
	v_pk_fma_f32 v[36:37], v[44:45], v[38:39], v[60:61] neg_lo:[0,0,1] neg_hi:[0,0,1]
	v_pk_fma_f32 v[38:39], v[44:45], v[38:39], v[60:61] op_sel_hi:[1,0,1]
	v_mov_b32_e32 v67, v41
	v_pk_mul_f32 v[42:43], v[46:47], v[64:65] op_sel:[1,0] op_sel_hi:[0,0]
	v_mov_b32_e32 v57, v33
	v_mov_b32_e32 v37, v39
	v_pk_mul_f32 v[38:39], v[48:49], v[66:67]
	v_pk_fma_f32 v[32:33], v[46:47], v[34:35], v[42:43] neg_lo:[0,0,1] neg_hi:[0,0,1]
	v_pk_fma_f32 v[34:35], v[46:47], v[62:63], v[42:43] op_sel_hi:[1,0,1]
	v_pk_mul_f32 v[40:41], v[50:51], v[56:57]
	v_sub_f32_e32 v31, v38, v39
	v_pk_mul_f32 v[36:37], v[52:53], v[36:37]
	v_mov_b32_e32 v33, v35
	v_sub_f32_e32 v34, v40, v41
	v_add_f32_e32 v6, v6, v31
	v_sub_f32_e32 v35, v36, v37
	v_pk_mul_f32 v[32:33], v[54:55], v[32:33]
	v_add_f32_e32 v6, v6, v34
	v_sub_f32_e32 v31, v32, v33
	v_add_f32_e32 v6, v6, v35
	v_add_f32_e32 v6, v6, v31
	v_lshl_add_u64 v[92:93], v[22:23], 0, s[8:9]
	v_lshl_add_u64 v[94:95], v[20:21], 0, s[8:9]
	v_lshl_add_u64 v[96:97], v[18:19], 0, s[8:9]
	v_lshl_add_u64 v[98:99], v[16:17], 0, s[8:9]
	global_load_dwordx4 v[148:151], v[92:93], off
	global_load_dwordx4 v[152:155], v[94:95], off
	global_load_dword v157, v[98:99], off
	global_load_dword v159, v[98:99], off offset:64
	global_load_dword v161, v[98:99], off offset:128
	global_load_dword v156, v[96:97], off
	global_load_dword v158, v[96:97], off offset:64
	global_load_dword v160, v[96:97], off offset:128
	global_load_dword v162, v[96:97], off offset:192
	global_load_dword v163, v[98:99], off offset:192
	v_lshl_add_u64 v[22:23], v[22:23], 0, 16
	v_lshl_add_u64 v[20:21], v[20:21], 0, 16
	v_lshl_add_u64 v[18:19], v[18:19], 0, s[20:21]
	v_lshl_add_u64 v[16:17], v[16:17], 0, s[20:21]
	s_waitcnt vmcnt(30)
	v_mov_b64_e32 v[32:33], v[100:101]
	v_mov_b64_e32 v[34:35], v[102:103]
	v_mov_b64_e32 v[36:37], v[104:105]
	v_mov_b64_e32 v[38:39], v[106:107]
	v_mov_b64_e32 v[48:49], v[108:109]
	v_mov_b64_e32 v[50:51], v[110:111]
	v_mov_b64_e32 v[52:53], v[112:113]
	v_mov_b64_e32 v[54:55], v[114:115]
	s_add_i32 s11, s10, 0
	v_mov_b32_e32 v31, s11
	ds_read_b128 v[40:43], v31
	ds_read_b128 v[44:47], v31 offset:16
	s_add_i32 s10, s10, 32
	s_waitcnt lgkmcnt(1)
	v_pk_mul_f32 v[56:57], v[40:41], v[32:33] op_sel:[1,0] op_sel_hi:[0,0]
	v_mov_b32_e32 v58, v37
	v_pk_mul_f32 v[32:33], v[42:43], v[32:33] op_sel:[1,1] op_sel_hi:[0,1]
	s_waitcnt lgkmcnt(0)
	v_pk_mul_f32 v[60:61], v[44:45], v[34:35] op_sel:[1,0] op_sel_hi:[0,0]
	v_pk_fma_f32 v[66:67], v[40:41], v[36:37], v[56:57] neg_lo:[0,0,1] neg_hi:[0,0,1]
	v_pk_fma_f32 v[40:41], v[40:41], v[36:37], v[56:57] op_sel_hi:[1,0,1]
	v_mov_b32_e32 v34, v39
	v_mov_b32_e32 v62, v39
	v_mov_b32_e32 v64, v35
	v_pk_fma_f32 v[56:57], v[42:43], v[58:59], v[32:33] neg_lo:[0,0,1] neg_hi:[0,0,1]
	v_pk_fma_f32 v[32:33], v[42:43], v[36:37], v[32:33] op_sel:[0,1,0]
	v_pk_fma_f32 v[36:37], v[44:45], v[38:39], v[60:61] neg_lo:[0,0,1] neg_hi:[0,0,1]
	v_pk_fma_f32 v[38:39], v[44:45], v[38:39], v[60:61] op_sel_hi:[1,0,1]
	v_mov_b32_e32 v67, v41
	v_pk_mul_f32 v[42:43], v[46:47], v[64:65] op_sel:[1,0] op_sel_hi:[0,0]
	v_mov_b32_e32 v57, v33
	v_mov_b32_e32 v37, v39
	v_pk_mul_f32 v[38:39], v[48:49], v[66:67]
	v_pk_fma_f32 v[32:33], v[46:47], v[34:35], v[42:43] neg_lo:[0,0,1] neg_hi:[0,0,1]
	v_pk_fma_f32 v[34:35], v[46:47], v[62:63], v[42:43] op_sel_hi:[1,0,1]
	v_pk_mul_f32 v[40:41], v[50:51], v[56:57]
	v_sub_f32_e32 v31, v38, v39
	v_pk_mul_f32 v[36:37], v[52:53], v[36:37]
	v_mov_b32_e32 v33, v35
	v_sub_f32_e32 v34, v40, v41
	v_add_f32_e32 v6, v6, v31
	v_sub_f32_e32 v35, v36, v37
	v_pk_mul_f32 v[32:33], v[54:55], v[32:33]
	v_add_f32_e32 v6, v6, v34
	v_sub_f32_e32 v31, v32, v33
	v_add_f32_e32 v6, v6, v35
	v_add_f32_e32 v6, v6, v31
	v_lshl_add_u64 v[92:93], v[22:23], 0, s[8:9]
	v_lshl_add_u64 v[94:95], v[20:21], 0, s[8:9]
	v_lshl_add_u64 v[96:97], v[18:19], 0, s[8:9]
	v_lshl_add_u64 v[98:99], v[16:17], 0, s[8:9]
	global_load_dwordx4 v[100:103], v[92:93], off
	global_load_dwordx4 v[104:107], v[94:95], off
	global_load_dword v109, v[98:99], off
	global_load_dword v111, v[98:99], off offset:64
	global_load_dword v113, v[98:99], off offset:128
	global_load_dword v108, v[96:97], off
	global_load_dword v110, v[96:97], off offset:64
	global_load_dword v112, v[96:97], off offset:128
	global_load_dword v114, v[96:97], off offset:192
	global_load_dword v115, v[98:99], off offset:192
	v_lshl_add_u64 v[22:23], v[22:23], 0, 16
	v_lshl_add_u64 v[20:21], v[20:21], 0, 16
	v_lshl_add_u64 v[18:19], v[18:19], 0, s[20:21]
	v_lshl_add_u64 v[16:17], v[16:17], 0, s[20:21]
	s_waitcnt vmcnt(30)
; __device__ __forceinline__ void phase0a(const int wvs, const Params& p, LAS unsigned char* lds) {
;     ...
;       if (tid < 256) { const int c = tid >> 4, cp = tid & 15; float s = 0.f;
;         const float* cre = p.in[I_CRE] + ((size_t)(l * 16 + g) * 16 + c) * 64; const float* cim = p.in[I_CIM] + ((size_t)(l * 16 + g) * 16 + c) * 64;
;         const float* bre = p.in[I_BRE] + ((size_t)(l * 16 + g) * 64) * 16 + cp; const float* bim = p.in[I_BIM] + ((size_t)(l * 16 + g) * 64) * 16 + cp;
;         for (int q = 0; q < 64; ++q) { const float tr = T[q * 2], ti = T[q * 2 + 1], xr = cre[q], xi = cim[q], yr = bre[q * 16], yi = bim[q * 16];
;           const float ur = xr * tr - xi * ti, ui = xr * ti + xi * tr; s += ur * yr - ui * yi; }
;         kd[(((size_t)(l * 2 + d) * 16 + g) * 16 + delta) * 256 + tid] = s; }
	v_mov_b64_e32 v[32:33], v[116:117]
	v_mov_b64_e32 v[34:35], v[118:119]
	v_mov_b64_e32 v[36:37], v[120:121]
	v_mov_b64_e32 v[38:39], v[122:123]
	v_mov_b64_e32 v[48:49], v[124:125]
	v_mov_b64_e32 v[50:51], v[126:127]
	v_mov_b64_e32 v[52:53], v[128:129]
	v_mov_b64_e32 v[54:55], v[130:131]
	s_add_i32 s11, s10, 0
	v_mov_b32_e32 v31, s11
	ds_read_b128 v[40:43], v31
	ds_read_b128 v[44:47], v31 offset:16
	s_add_i32 s10, s10, 32
	s_waitcnt lgkmcnt(1)
	v_pk_mul_f32 v[56:57], v[40:41], v[32:33] op_sel:[1,0] op_sel_hi:[0,0]
	v_mov_b32_e32 v58, v37
	v_pk_mul_f32 v[32:33], v[42:43], v[32:33] op_sel:[1,1] op_sel_hi:[0,1]
	s_waitcnt lgkmcnt(0)
	v_pk_mul_f32 v[60:61], v[44:45], v[34:35] op_sel:[1,0] op_sel_hi:[0,0]
	v_pk_fma_f32 v[66:67], v[40:41], v[36:37], v[56:57] neg_lo:[0,0,1] neg_hi:[0,0,1]
	v_pk_fma_f32 v[40:41], v[40:41], v[36:37], v[56:57] op_sel_hi:[1,0,1]
	v_mov_b32_e32 v34, v39
	v_mov_b32_e32 v62, v39
	v_mov_b32_e32 v64, v35
	v_pk_fma_f32 v[56:57], v[42:43], v[58:59], v[32:33] neg_lo:[0,0,1] neg_hi:[0,0,1]
	v_pk_fma_f32 v[32:33], v[42:43], v[36:37], v[32:33] op_sel:[0,1,0]
	v_pk_fma_f32 v[36:37], v[44:45], v[38:39], v[60:61] neg_lo:[0,0,1] neg_hi:[0,0,1]
	v_pk_fma_f32 v[38:39], v[44:45], v[38:39], v[60:61] op_sel_hi:[1,0,1]
	v_mov_b32_e32 v67, v41
	v_pk_mul_f32 v[42:43], v[46:47], v[64:65] op_sel:[1,0] op_sel_hi:[0,0]
	v_mov_b32_e32 v57, v33
	v_mov_b32_e32 v37, v39
	v_pk_mul_f32 v[38:39], v[48:49], v[66:67]
	v_pk_fma_f32 v[32:33], v[46:47], v[34:35], v[42:43] neg_lo:[0,0,1] neg_hi:[0,0,1]
	v_pk_fma_f32 v[34:35], v[46:47], v[62:63], v[42:43] op_sel_hi:[1,0,1]
	v_pk_mul_f32 v[40:41], v[50:51], v[56:57]
	v_sub_f32_e32 v31, v38, v39
	v_pk_mul_f32 v[36:37], v[52:53], v[36:37]
	v_mov_b32_e32 v33, v35
	v_sub_f32_e32 v34, v40, v41
	v_add_f32_e32 v6, v6, v31
	v_sub_f32_e32 v35, v36, v37
	v_pk_mul_f32 v[32:33], v[54:55], v[32:33]
	v_add_f32_e32 v6, v6, v34
	v_sub_f32_e32 v31, v32, v33
	v_add_f32_e32 v6, v6, v35
	v_add_f32_e32 v6, v6, v31
	v_lshl_add_u64 v[92:93], v[22:23], 0, s[8:9]
	v_lshl_add_u64 v[94:95], v[20:21], 0, s[8:9]
	v_lshl_add_u64 v[96:97], v[18:19], 0, s[8:9]
	v_lshl_add_u64 v[98:99], v[16:17], 0, s[8:9]
	global_load_dwordx4 v[116:119], v[92:93], off
	global_load_dwordx4 v[120:123], v[94:95], off
	global_load_dword v125, v[98:99], off
	global_load_dword v127, v[98:99], off offset:64
	global_load_dword v129, v[98:99], off offset:128
	global_load_dword v124, v[96:97], off
	global_load_dword v126, v[96:97], off offset:64
	global_load_dword v128, v[96:97], off offset:128
	global_load_dword v130, v[96:97], off offset:192
	global_load_dword v131, v[98:99], off offset:192
	v_lshl_add_u64 v[22:23], v[22:23], 0, 16
	v_lshl_add_u64 v[20:21], v[20:21], 0, 16
	v_lshl_add_u64 v[18:19], v[18:19], 0, s[20:21]
	v_lshl_add_u64 v[16:17], v[16:17], 0, s[20:21]
	s_waitcnt vmcnt(30)
	v_mov_b64_e32 v[32:33], v[132:133]
	v_mov_b64_e32 v[34:35], v[134:135]
	v_mov_b64_e32 v[36:37], v[136:137]
	v_mov_b64_e32 v[38:39], v[138:139]
	v_mov_b64_e32 v[48:49], v[140:141]
	v_mov_b64_e32 v[50:51], v[142:143]
	v_mov_b64_e32 v[52:53], v[144:145]
	v_mov_b64_e32 v[54:55], v[146:147]
	s_add_i32 s11, s10, 0
	v_mov_b32_e32 v31, s11
	ds_read_b128 v[40:43], v31
	ds_read_b128 v[44:47], v31 offset:16
	s_add_i32 s10, s10, 32
	s_waitcnt lgkmcnt(1)
	v_pk_mul_f32 v[56:57], v[40:41], v[32:33] op_sel:[1,0] op_sel_hi:[0,0]
	v_mov_b32_e32 v58, v37
	v_pk_mul_f32 v[32:33], v[42:43], v[32:33] op_sel:[1,1] op_sel_hi:[0,1]
	s_waitcnt lgkmcnt(0)
	v_pk_mul_f32 v[60:61], v[44:45], v[34:35] op_sel:[1,0] op_sel_hi:[0,0]
	v_pk_fma_f32 v[66:67], v[40:41], v[36:37], v[56:57] neg_lo:[0,0,1] neg_hi:[0,0,1]
	v_pk_fma_f32 v[40:41], v[40:41], v[36:37], v[56:57] op_sel_hi:[1,0,1]
	v_mov_b32_e32 v34, v39
	v_mov_b32_e32 v62, v39
	v_mov_b32_e32 v64, v35
	v_pk_fma_f32 v[56:57], v[42:43], v[58:59], v[32:33] neg_lo:[0,0,1] neg_hi:[0,0,1]
	v_pk_fma_f32 v[32:33], v[42:43], v[36:37], v[32:33] op_sel:[0,1,0]
	v_pk_fma_f32 v[36:37], v[44:45], v[38:39], v[60:61] neg_lo:[0,0,1] neg_hi:[0,0,1]
	v_pk_fma_f32 v[38:39], v[44:45], v[38:39], v[60:61] op_sel_hi:[1,0,1]
	v_mov_b32_e32 v67, v41
	v_pk_mul_f32 v[42:43], v[46:47], v[64:65] op_sel:[1,0] op_sel_hi:[0,0]
	v_mov_b32_e32 v57, v33
	v_mov_b32_e32 v37, v39
	v_pk_mul_f32 v[38:39], v[48:49], v[66:67]
	v_pk_fma_f32 v[32:33], v[46:47], v[34:35], v[42:43] neg_lo:[0,0,1] neg_hi:[0,0,1]
	v_pk_fma_f32 v[34:35], v[46:47], v[62:63], v[42:43] op_sel_hi:[1,0,1]
	v_pk_mul_f32 v[40:41], v[50:51], v[56:57]
	v_sub_f32_e32 v31, v38, v39
	v_pk_mul_f32 v[36:37], v[52:53], v[36:37]
	v_mov_b32_e32 v33, v35
	v_sub_f32_e32 v34, v40, v41
	v_add_f32_e32 v6, v6, v31
	v_sub_f32_e32 v35, v36, v37
	v_pk_mul_f32 v[32:33], v[54:55], v[32:33]
	v_add_f32_e32 v6, v6, v34
	v_sub_f32_e32 v31, v32, v33
	v_add_f32_e32 v6, v6, v35
	v_add_f32_e32 v6, v6, v31
	v_lshl_add_u64 v[92:93], v[22:23], 0, s[8:9]
	v_lshl_add_u64 v[94:95], v[20:21], 0, s[8:9]
	v_lshl_add_u64 v[96:97], v[18:19], 0, s[8:9]
	v_lshl_add_u64 v[98:99], v[16:17], 0, s[8:9]
	global_load_dwordx4 v[132:135], v[92:93], off
	global_load_dwordx4 v[136:139], v[94:95], off
	global_load_dword v141, v[98:99], off
	global_load_dword v143, v[98:99], off offset:64
	global_load_dword v145, v[98:99], off offset:128
	global_load_dword v140, v[96:97], off
	global_load_dword v142, v[96:97], off offset:64
	global_load_dword v144, v[96:97], off offset:128
	global_load_dword v146, v[96:97], off offset:192
	global_load_dword v147, v[98:99], off offset:192
	v_lshl_add_u64 v[22:23], v[22:23], 0, 16
	v_lshl_add_u64 v[20:21], v[20:21], 0, 16
	v_lshl_add_u64 v[18:19], v[18:19], 0, s[20:21]
	v_lshl_add_u64 v[16:17], v[16:17], 0, s[20:21]
	s_waitcnt vmcnt(30)
; __device__ __forceinline__ void phase0a(const int wvs, const Params& p, LAS unsigned char* lds) {
;     ...
;       if (tid < 256) { const int c = tid >> 4, cp = tid & 15; float s = 0.f;
;         const float* cre = p.in[I_CRE] + ((size_t)(l * 16 + g) * 16 + c) * 64; const float* cim = p.in[I_CIM] + ((size_t)(l * 16 + g) * 16 + c) * 64;
;         const float* bre = p.in[I_BRE] + ((size_t)(l * 16 + g) * 64) * 16 + cp; const float* bim = p.in[I_BIM] + ((size_t)(l * 16 + g) * 64) * 16 + cp;
;         for (int q = 0; q < 64; ++q) { const float tr = T[q * 2], ti = T[q * 2 + 1], xr = cre[q], xi = cim[q], yr = bre[q * 16], yi = bim[q * 16];
;           const float ur = xr * tr - xi * ti, ui = xr * ti + xi * tr; s += ur * yr - ui * yi; }
;         kd[(((size_t)(l * 2 + d) * 16 + g) * 16 + delta) * 256 + tid] = s; }
	v_mov_b64_e32 v[32:33], v[148:149]
	v_mov_b64_e32 v[34:35], v[150:151]
	v_mov_b64_e32 v[36:37], v[152:153]
	v_mov_b64_e32 v[38:39], v[154:155]
	v_mov_b64_e32 v[48:49], v[156:157]
	v_mov_b64_e32 v[50:51], v[158:159]
	v_mov_b64_e32 v[52:53], v[160:161]
	v_mov_b64_e32 v[54:55], v[162:163]
	s_add_i32 s11, s10, 0
	v_mov_b32_e32 v31, s11
	ds_read_b128 v[40:43], v31
	ds_read_b128 v[44:47], v31 offset:16
	s_add_i32 s10, s10, 32
	s_waitcnt lgkmcnt(1)
	v_pk_mul_f32 v[56:57], v[40:41], v[32:33] op_sel:[1,0] op_sel_hi:[0,0]
	v_mov_b32_e32 v58, v37
	v_pk_mul_f32 v[32:33], v[42:43], v[32:33] op_sel:[1,1] op_sel_hi:[0,1]
	s_waitcnt lgkmcnt(0)
	v_pk_mul_f32 v[60:61], v[44:45], v[34:35] op_sel:[1,0] op_sel_hi:[0,0]
	v_pk_fma_f32 v[66:67], v[40:41], v[36:37], v[56:57] neg_lo:[0,0,1] neg_hi:[0,0,1]
	v_pk_fma_f32 v[40:41], v[40:41], v[36:37], v[56:57] op_sel_hi:[1,0,1]
	v_mov_b32_e32 v34, v39
	v_mov_b32_e32 v62, v39
	v_mov_b32_e32 v64, v35
	v_pk_fma_f32 v[56:57], v[42:43], v[58:59], v[32:33] neg_lo:[0,0,1] neg_hi:[0,0,1]
	v_pk_fma_f32 v[32:33], v[42:43], v[36:37], v[32:33] op_sel:[0,1,0]
	v_pk_fma_f32 v[36:37], v[44:45], v[38:39], v[60:61] neg_lo:[0,0,1] neg_hi:[0,0,1]
	v_pk_fma_f32 v[38:39], v[44:45], v[38:39], v[60:61] op_sel_hi:[1,0,1]
	v_mov_b32_e32 v67, v41
	v_pk_mul_f32 v[42:43], v[46:47], v[64:65] op_sel:[1,0] op_sel_hi:[0,0]
	v_mov_b32_e32 v57, v33
	v_mov_b32_e32 v37, v39
	v_pk_mul_f32 v[38:39], v[48:49], v[66:67]
	v_pk_fma_f32 v[32:33], v[46:47], v[34:35], v[42:43] neg_lo:[0,0,1] neg_hi:[0,0,1]
	v_pk_fma_f32 v[34:35], v[46:47], v[62:63], v[42:43] op_sel_hi:[1,0,1]
	v_pk_mul_f32 v[40:41], v[50:51], v[56:57]
	v_sub_f32_e32 v31, v38, v39
	v_pk_mul_f32 v[36:37], v[52:53], v[36:37]
	v_mov_b32_e32 v33, v35
	v_sub_f32_e32 v34, v40, v41
	v_add_f32_e32 v6, v6, v31
	v_sub_f32_e32 v35, v36, v37
	v_pk_mul_f32 v[32:33], v[54:55], v[32:33]
	v_add_f32_e32 v6, v6, v34
	v_sub_f32_e32 v31, v32, v33
	v_add_f32_e32 v6, v6, v35
	v_add_f32_e32 v6, v6, v31
	v_lshl_add_u64 v[92:93], v[22:23], 0, s[8:9]
	v_lshl_add_u64 v[94:95], v[20:21], 0, s[8:9]
	v_lshl_add_u64 v[96:97], v[18:19], 0, s[8:9]
	v_lshl_add_u64 v[98:99], v[16:17], 0, s[8:9]
	global_load_dwordx4 v[148:151], v[92:93], off
	global_load_dwordx4 v[152:155], v[94:95], off
	global_load_dword v157, v[98:99], off
	global_load_dword v159, v[98:99], off offset:64
	global_load_dword v161, v[98:99], off offset:128
	global_load_dword v156, v[96:97], off
	global_load_dword v158, v[96:97], off offset:64
	global_load_dword v160, v[96:97], off offset:128
	global_load_dword v162, v[96:97], off offset:192
	global_load_dword v163, v[98:99], off offset:192
	v_lshl_add_u64 v[22:23], v[22:23], 0, 16
	v_lshl_add_u64 v[20:21], v[20:21], 0, 16
	v_lshl_add_u64 v[18:19], v[18:19], 0, s[20:21]
	v_lshl_add_u64 v[16:17], v[16:17], 0, s[20:21]
	s_waitcnt vmcnt(30)
	v_mov_b64_e32 v[32:33], v[100:101]
	v_mov_b64_e32 v[34:35], v[102:103]
	v_mov_b64_e32 v[36:37], v[104:105]
	v_mov_b64_e32 v[38:39], v[106:107]
	v_mov_b64_e32 v[48:49], v[108:109]
	v_mov_b64_e32 v[50:51], v[110:111]
	v_mov_b64_e32 v[52:53], v[112:113]
	v_mov_b64_e32 v[54:55], v[114:115]
	s_add_i32 s11, s10, 0
	v_mov_b32_e32 v31, s11
	ds_read_b128 v[40:43], v31
	ds_read_b128 v[44:47], v31 offset:16
	s_add_i32 s10, s10, 32
	s_waitcnt lgkmcnt(1)
	v_pk_mul_f32 v[56:57], v[40:41], v[32:33] op_sel:[1,0] op_sel_hi:[0,0]
	v_mov_b32_e32 v58, v37
	v_pk_mul_f32 v[32:33], v[42:43], v[32:33] op_sel:[1,1] op_sel_hi:[0,1]
	s_waitcnt lgkmcnt(0)
	v_pk_mul_f32 v[60:61], v[44:45], v[34:35] op_sel:[1,0] op_sel_hi:[0,0]
	v_pk_fma_f32 v[66:67], v[40:41], v[36:37], v[56:57] neg_lo:[0,0,1] neg_hi:[0,0,1]
	v_pk_fma_f32 v[40:41], v[40:41], v[36:37], v[56:57] op_sel_hi:[1,0,1]
	v_mov_b32_e32 v34, v39
	v_mov_b32_e32 v62, v39
	v_mov_b32_e32 v64, v35
	v_pk_fma_f32 v[56:57], v[42:43], v[58:59], v[32:33] neg_lo:[0,0,1] neg_hi:[0,0,1]
	v_pk_fma_f32 v[32:33], v[42:43], v[36:37], v[32:33] op_sel:[0,1,0]
	v_pk_fma_f32 v[36:37], v[44:45], v[38:39], v[60:61] neg_lo:[0,0,1] neg_hi:[0,0,1]
	v_pk_fma_f32 v[38:39], v[44:45], v[38:39], v[60:61] op_sel_hi:[1,0,1]
	v_mov_b32_e32 v67, v41
	v_pk_mul_f32 v[42:43], v[46:47], v[64:65] op_sel:[1,0] op_sel_hi:[0,0]
	v_mov_b32_e32 v57, v33
	v_mov_b32_e32 v37, v39
	v_pk_mul_f32 v[38:39], v[48:49], v[66:67]
	v_pk_fma_f32 v[32:33], v[46:47], v[34:35], v[42:43] neg_lo:[0,0,1] neg_hi:[0,0,1]
	v_pk_fma_f32 v[34:35], v[46:47], v[62:63], v[42:43] op_sel_hi:[1,0,1]
	v_pk_mul_f32 v[40:41], v[50:51], v[56:57]
	v_sub_f32_e32 v31, v38, v39
	v_pk_mul_f32 v[36:37], v[52:53], v[36:37]
	v_mov_b32_e32 v33, v35
	v_sub_f32_e32 v34, v40, v41
	v_add_f32_e32 v6, v6, v31
	v_sub_f32_e32 v35, v36, v37
	v_pk_mul_f32 v[32:33], v[54:55], v[32:33]
	v_add_f32_e32 v6, v6, v34
	v_sub_f32_e32 v31, v32, v33
	v_add_f32_e32 v6, v6, v35
	v_add_f32_e32 v6, v6, v31
	v_lshl_add_u64 v[92:93], v[22:23], 0, s[8:9]
	v_lshl_add_u64 v[94:95], v[20:21], 0, s[8:9]
	v_lshl_add_u64 v[96:97], v[18:19], 0, s[8:9]
	v_lshl_add_u64 v[98:99], v[16:17], 0, s[8:9]
	global_load_dwordx4 v[100:103], v[92:93], off
	global_load_dwordx4 v[104:107], v[94:95], off
	global_load_dword v109, v[98:99], off
	global_load_dword v111, v[98:99], off offset:64
	global_load_dword v113, v[98:99], off offset:128
	global_load_dword v108, v[96:97], off
	global_load_dword v110, v[96:97], off offset:64
	global_load_dword v112, v[96:97], off offset:128
	global_load_dword v114, v[96:97], off offset:192
	global_load_dword v115, v[98:99], off offset:192
	v_lshl_add_u64 v[22:23], v[22:23], 0, 16
	v_lshl_add_u64 v[20:21], v[20:21], 0, 16
	v_lshl_add_u64 v[18:19], v[18:19], 0, s[20:21]
	v_lshl_add_u64 v[16:17], v[16:17], 0, s[20:21]
	s_waitcnt vmcnt(30)
; __device__ __forceinline__ void phase0a(const int wvs, const Params& p, LAS unsigned char* lds) {
;     ...
;       if (tid < 256) { const int c = tid >> 4, cp = tid & 15; float s = 0.f;
;         const float* cre = p.in[I_CRE] + ((size_t)(l * 16 + g) * 16 + c) * 64; const float* cim = p.in[I_CIM] + ((size_t)(l * 16 + g) * 16 + c) * 64;
;         const float* bre = p.in[I_BRE] + ((size_t)(l * 16 + g) * 64) * 16 + cp; const float* bim = p.in[I_BIM] + ((size_t)(l * 16 + g) * 64) * 16 + cp;
;         for (int q = 0; q < 64; ++q) { const float tr = T[q * 2], ti = T[q * 2 + 1], xr = cre[q], xi = cim[q], yr = bre[q * 16], yi = bim[q * 16];
;           const float ur = xr * tr - xi * ti, ui = xr * ti + xi * tr; s += ur * yr - ui * yi; }
;         kd[(((size_t)(l * 2 + d) * 16 + g) * 16 + delta) * 256 + tid] = s; }
	v_mov_b64_e32 v[32:33], v[116:117]
	v_mov_b64_e32 v[34:35], v[118:119]
	v_mov_b64_e32 v[36:37], v[120:121]
	v_mov_b64_e32 v[38:39], v[122:123]
	v_mov_b64_e32 v[48:49], v[124:125]
	v_mov_b64_e32 v[50:51], v[126:127]
	v_mov_b64_e32 v[52:53], v[128:129]
	v_mov_b64_e32 v[54:55], v[130:131]
	s_add_i32 s11, s10, 0
	v_mov_b32_e32 v31, s11
	ds_read_b128 v[40:43], v31
	ds_read_b128 v[44:47], v31 offset:16
	s_add_i32 s10, s10, 32
	s_waitcnt lgkmcnt(1)
	v_pk_mul_f32 v[56:57], v[40:41], v[32:33] op_sel:[1,0] op_sel_hi:[0,0]
	v_mov_b32_e32 v58, v37
	v_pk_mul_f32 v[32:33], v[42:43], v[32:33] op_sel:[1,1] op_sel_hi:[0,1]
	s_waitcnt lgkmcnt(0)
	v_pk_mul_f32 v[60:61], v[44:45], v[34:35] op_sel:[1,0] op_sel_hi:[0,0]
	v_pk_fma_f32 v[66:67], v[40:41], v[36:37], v[56:57] neg_lo:[0,0,1] neg_hi:[0,0,1]
	v_pk_fma_f32 v[40:41], v[40:41], v[36:37], v[56:57] op_sel_hi:[1,0,1]
	v_mov_b32_e32 v34, v39
	v_mov_b32_e32 v62, v39
	v_mov_b32_e32 v64, v35
	v_pk_fma_f32 v[56:57], v[42:43], v[58:59], v[32:33] neg_lo:[0,0,1] neg_hi:[0,0,1]
	v_pk_fma_f32 v[32:33], v[42:43], v[36:37], v[32:33] op_sel:[0,1,0]
	v_pk_fma_f32 v[36:37], v[44:45], v[38:39], v[60:61] neg_lo:[0,0,1] neg_hi:[0,0,1]
	v_pk_fma_f32 v[38:39], v[44:45], v[38:39], v[60:61] op_sel_hi:[1,0,1]
	v_mov_b32_e32 v67, v41
	v_pk_mul_f32 v[42:43], v[46:47], v[64:65] op_sel:[1,0] op_sel_hi:[0,0]
	v_mov_b32_e32 v57, v33
	v_mov_b32_e32 v37, v39
	v_pk_mul_f32 v[38:39], v[48:49], v[66:67]
	v_pk_fma_f32 v[32:33], v[46:47], v[34:35], v[42:43] neg_lo:[0,0,1] neg_hi:[0,0,1]
	v_pk_fma_f32 v[34:35], v[46:47], v[62:63], v[42:43] op_sel_hi:[1,0,1]
	v_pk_mul_f32 v[40:41], v[50:51], v[56:57]
	v_sub_f32_e32 v31, v38, v39
	v_pk_mul_f32 v[36:37], v[52:53], v[36:37]
	v_mov_b32_e32 v33, v35
	v_sub_f32_e32 v34, v40, v41
	v_add_f32_e32 v6, v6, v31
	v_sub_f32_e32 v35, v36, v37
	v_pk_mul_f32 v[32:33], v[54:55], v[32:33]
	v_add_f32_e32 v6, v6, v34
	v_sub_f32_e32 v31, v32, v33
	v_add_f32_e32 v6, v6, v35
	v_add_f32_e32 v6, v6, v31
	v_lshl_add_u64 v[92:93], v[22:23], 0, s[8:9]
	v_lshl_add_u64 v[94:95], v[20:21], 0, s[8:9]
	v_lshl_add_u64 v[96:97], v[18:19], 0, s[8:9]
	v_lshl_add_u64 v[98:99], v[16:17], 0, s[8:9]
	global_load_dwordx4 v[116:119], v[92:93], off
	global_load_dwordx4 v[120:123], v[94:95], off
	global_load_dword v125, v[98:99], off
	global_load_dword v127, v[98:99], off offset:64
	global_load_dword v129, v[98:99], off offset:128
	global_load_dword v124, v[96:97], off
	global_load_dword v126, v[96:97], off offset:64
	global_load_dword v128, v[96:97], off offset:128
	global_load_dword v130, v[96:97], off offset:192
	global_load_dword v131, v[98:99], off offset:192
	v_lshl_add_u64 v[22:23], v[22:23], 0, 16
	v_lshl_add_u64 v[20:21], v[20:21], 0, 16
	v_lshl_add_u64 v[18:19], v[18:19], 0, s[20:21]
	v_lshl_add_u64 v[16:17], v[16:17], 0, s[20:21]
	s_waitcnt vmcnt(30)
	v_mov_b64_e32 v[32:33], v[132:133]
	v_mov_b64_e32 v[34:35], v[134:135]
	v_mov_b64_e32 v[36:37], v[136:137]
	v_mov_b64_e32 v[38:39], v[138:139]
	v_mov_b64_e32 v[48:49], v[140:141]
	v_mov_b64_e32 v[50:51], v[142:143]
	v_mov_b64_e32 v[52:53], v[144:145]
	v_mov_b64_e32 v[54:55], v[146:147]
	s_add_i32 s11, s10, 0
	v_mov_b32_e32 v31, s11
	ds_read_b128 v[40:43], v31
	ds_read_b128 v[44:47], v31 offset:16
	s_add_i32 s10, s10, 32
	s_waitcnt lgkmcnt(1)
	v_pk_mul_f32 v[56:57], v[40:41], v[32:33] op_sel:[1,0] op_sel_hi:[0,0]
	v_mov_b32_e32 v58, v37
	v_pk_mul_f32 v[32:33], v[42:43], v[32:33] op_sel:[1,1] op_sel_hi:[0,1]
	s_waitcnt lgkmcnt(0)
	v_pk_mul_f32 v[60:61], v[44:45], v[34:35] op_sel:[1,0] op_sel_hi:[0,0]
	v_pk_fma_f32 v[66:67], v[40:41], v[36:37], v[56:57] neg_lo:[0,0,1] neg_hi:[0,0,1]
	v_pk_fma_f32 v[40:41], v[40:41], v[36:37], v[56:57] op_sel_hi:[1,0,1]
	v_mov_b32_e32 v34, v39
	v_mov_b32_e32 v62, v39
	v_mov_b32_e32 v64, v35
	v_pk_fma_f32 v[56:57], v[42:43], v[58:59], v[32:33] neg_lo:[0,0,1] neg_hi:[0,0,1]
	v_pk_fma_f32 v[32:33], v[42:43], v[36:37], v[32:33] op_sel:[0,1,0]
	v_pk_fma_f32 v[36:37], v[44:45], v[38:39], v[60:61] neg_lo:[0,0,1] neg_hi:[0,0,1]
	v_pk_fma_f32 v[38:39], v[44:45], v[38:39], v[60:61] op_sel_hi:[1,0,1]
	v_mov_b32_e32 v67, v41
	v_pk_mul_f32 v[42:43], v[46:47], v[64:65] op_sel:[1,0] op_sel_hi:[0,0]
	v_mov_b32_e32 v57, v33
	v_mov_b32_e32 v37, v39
	v_pk_mul_f32 v[38:39], v[48:49], v[66:67]
	v_pk_fma_f32 v[32:33], v[46:47], v[34:35], v[42:43] neg_lo:[0,0,1] neg_hi:[0,0,1]
	v_pk_fma_f32 v[34:35], v[46:47], v[62:63], v[42:43] op_sel_hi:[1,0,1]
	v_pk_mul_f32 v[40:41], v[50:51], v[56:57]
	v_sub_f32_e32 v31, v38, v39
	v_pk_mul_f32 v[36:37], v[52:53], v[36:37]
	v_mov_b32_e32 v33, v35
	v_sub_f32_e32 v34, v40, v41
	v_add_f32_e32 v6, v6, v31
	v_sub_f32_e32 v35, v36, v37
	v_pk_mul_f32 v[32:33], v[54:55], v[32:33]
	v_add_f32_e32 v6, v6, v34
	v_sub_f32_e32 v31, v32, v33
	v_add_f32_e32 v6, v6, v35
	v_add_f32_e32 v6, v6, v31
	v_lshl_add_u64 v[92:93], v[22:23], 0, s[8:9]
	v_lshl_add_u64 v[94:95], v[20:21], 0, s[8:9]
	v_lshl_add_u64 v[96:97], v[18:19], 0, s[8:9]
	v_lshl_add_u64 v[98:99], v[16:17], 0, s[8:9]
	global_load_dwordx4 v[132:135], v[92:93], off
	global_load_dwordx4 v[136:139], v[94:95], off
	global_load_dword v141, v[98:99], off
	global_load_dword v143, v[98:99], off offset:64
	global_load_dword v145, v[98:99], off offset:128
	global_load_dword v140, v[96:97], off
	global_load_dword v142, v[96:97], off offset:64
	global_load_dword v144, v[96:97], off offset:128
	global_load_dword v146, v[96:97], off offset:192
	global_load_dword v147, v[98:99], off offset:192
	v_lshl_add_u64 v[22:23], v[22:23], 0, 16
	v_lshl_add_u64 v[20:21], v[20:21], 0, 16
	v_lshl_add_u64 v[18:19], v[18:19], 0, s[20:21]
	v_lshl_add_u64 v[16:17], v[16:17], 0, s[20:21]
	s_waitcnt vmcnt(30)
; __device__ __forceinline__ void phase0a(const int wvs, const Params& p, LAS unsigned char* lds) {
;     ...
;       if (tid < 256) { const int c = tid >> 4, cp = tid & 15; float s = 0.f;
;         const float* cre = p.in[I_CRE] + ((size_t)(l * 16 + g) * 16 + c) * 64; const float* cim = p.in[I_CIM] + ((size_t)(l * 16 + g) * 16 + c) * 64;
;         const float* bre = p.in[I_BRE] + ((size_t)(l * 16 + g) * 64) * 16 + cp; const float* bim = p.in[I_BIM] + ((size_t)(l * 16 + g) * 64) * 16 + cp;
;         for (int q = 0; q < 64; ++q) { const float tr = T[q * 2], ti = T[q * 2 + 1], xr = cre[q], xi = cim[q], yr = bre[q * 16], yi = bim[q * 16];
;           const float ur = xr * tr - xi * ti, ui = xr * ti + xi * tr; s += ur * yr - ui * yi; }
;         kd[(((size_t)(l * 2 + d) * 16 + g) * 16 + delta) * 256 + tid] = s; }
	v_mov_b64_e32 v[32:33], v[148:149]
	v_mov_b64_e32 v[34:35], v[150:151]
	v_mov_b64_e32 v[36:37], v[152:153]
	v_mov_b64_e32 v[38:39], v[154:155]
	v_mov_b64_e32 v[48:49], v[156:157]
	v_mov_b64_e32 v[50:51], v[158:159]
	v_mov_b64_e32 v[52:53], v[160:161]
	v_mov_b64_e32 v[54:55], v[162:163]
	s_add_i32 s11, s10, 0
	v_mov_b32_e32 v31, s11
	ds_read_b128 v[40:43], v31
	ds_read_b128 v[44:47], v31 offset:16
	s_add_i32 s10, s10, 32
	s_waitcnt lgkmcnt(1)
	v_pk_mul_f32 v[56:57], v[40:41], v[32:33] op_sel:[1,0] op_sel_hi:[0,0]
	v_mov_b32_e32 v58, v37
	v_pk_mul_f32 v[32:33], v[42:43], v[32:33] op_sel:[1,1] op_sel_hi:[0,1]
	s_waitcnt lgkmcnt(0)
	v_pk_mul_f32 v[60:61], v[44:45], v[34:35] op_sel:[1,0] op_sel_hi:[0,0]
	v_pk_fma_f32 v[66:67], v[40:41], v[36:37], v[56:57] neg_lo:[0,0,1] neg_hi:[0,0,1]
	v_pk_fma_f32 v[40:41], v[40:41], v[36:37], v[56:57] op_sel_hi:[1,0,1]
	v_mov_b32_e32 v34, v39
	v_mov_b32_e32 v62, v39
	v_mov_b32_e32 v64, v35
	v_pk_fma_f32 v[56:57], v[42:43], v[58:59], v[32:33] neg_lo:[0,0,1] neg_hi:[0,0,1]
	v_pk_fma_f32 v[32:33], v[42:43], v[36:37], v[32:33] op_sel:[0,1,0]
	v_pk_fma_f32 v[36:37], v[44:45], v[38:39], v[60:61] neg_lo:[0,0,1] neg_hi:[0,0,1]
	v_pk_fma_f32 v[38:39], v[44:45], v[38:39], v[60:61] op_sel_hi:[1,0,1]
	v_mov_b32_e32 v67, v41
	v_pk_mul_f32 v[42:43], v[46:47], v[64:65] op_sel:[1,0] op_sel_hi:[0,0]
	v_mov_b32_e32 v57, v33
	v_mov_b32_e32 v37, v39
	v_pk_mul_f32 v[38:39], v[48:49], v[66:67]
	v_pk_fma_f32 v[32:33], v[46:47], v[34:35], v[42:43] neg_lo:[0,0,1] neg_hi:[0,0,1]
	v_pk_fma_f32 v[34:35], v[46:47], v[62:63], v[42:43] op_sel_hi:[1,0,1]
	v_pk_mul_f32 v[40:41], v[50:51], v[56:57]
	v_sub_f32_e32 v31, v38, v39
	v_pk_mul_f32 v[36:37], v[52:53], v[36:37]
	v_mov_b32_e32 v33, v35
	v_sub_f32_e32 v34, v40, v41
	v_add_f32_e32 v6, v6, v31
	v_sub_f32_e32 v35, v36, v37
	v_pk_mul_f32 v[32:33], v[54:55], v[32:33]
	v_add_f32_e32 v6, v6, v34
	v_sub_f32_e32 v31, v32, v33
	v_add_f32_e32 v6, v6, v35
	v_add_f32_e32 v6, v6, v31
	v_lshl_add_u64 v[92:93], v[22:23], 0, s[8:9]
	v_lshl_add_u64 v[94:95], v[20:21], 0, s[8:9]
	v_lshl_add_u64 v[96:97], v[18:19], 0, s[8:9]
	v_lshl_add_u64 v[98:99], v[16:17], 0, s[8:9]
	global_load_dwordx4 v[148:151], v[92:93], off
	global_load_dwordx4 v[152:155], v[94:95], off
	global_load_dword v157, v[98:99], off
	global_load_dword v159, v[98:99], off offset:64
	global_load_dword v161, v[98:99], off offset:128
	global_load_dword v156, v[96:97], off
	global_load_dword v158, v[96:97], off offset:64
	global_load_dword v160, v[96:97], off offset:128
	global_load_dword v162, v[96:97], off offset:192
	global_load_dword v163, v[98:99], off offset:192
	v_lshl_add_u64 v[22:23], v[22:23], 0, 16
	v_lshl_add_u64 v[20:21], v[20:21], 0, 16
	v_lshl_add_u64 v[18:19], v[18:19], 0, s[20:21]
	v_lshl_add_u64 v[16:17], v[16:17], 0, s[20:21]
	s_waitcnt vmcnt(30)
	v_mov_b64_e32 v[32:33], v[100:101]
	v_mov_b64_e32 v[34:35], v[102:103]
	v_mov_b64_e32 v[36:37], v[104:105]
	v_mov_b64_e32 v[38:39], v[106:107]
	v_mov_b64_e32 v[48:49], v[108:109]
	v_mov_b64_e32 v[50:51], v[110:111]
	v_mov_b64_e32 v[52:53], v[112:113]
	v_mov_b64_e32 v[54:55], v[114:115]
	s_add_i32 s11, s10, 0
	v_mov_b32_e32 v31, s11
	ds_read_b128 v[40:43], v31
	ds_read_b128 v[44:47], v31 offset:16
	s_add_i32 s10, s10, 32
	s_waitcnt lgkmcnt(1)
	v_pk_mul_f32 v[56:57], v[40:41], v[32:33] op_sel:[1,0] op_sel_hi:[0,0]
	v_mov_b32_e32 v58, v37
	v_pk_mul_f32 v[32:33], v[42:43], v[32:33] op_sel:[1,1] op_sel_hi:[0,1]
	s_waitcnt lgkmcnt(0)
	v_pk_mul_f32 v[60:61], v[44:45], v[34:35] op_sel:[1,0] op_sel_hi:[0,0]
	v_pk_fma_f32 v[66:67], v[40:41], v[36:37], v[56:57] neg_lo:[0,0,1] neg_hi:[0,0,1]
	v_pk_fma_f32 v[40:41], v[40:41], v[36:37], v[56:57] op_sel_hi:[1,0,1]
	v_mov_b32_e32 v34, v39
	v_mov_b32_e32 v62, v39
	v_mov_b32_e32 v64, v35
	v_pk_fma_f32 v[56:57], v[42:43], v[58:59], v[32:33] neg_lo:[0,0,1] neg_hi:[0,0,1]
	v_pk_fma_f32 v[32:33], v[42:43], v[36:37], v[32:33] op_sel:[0,1,0]
	v_pk_fma_f32 v[36:37], v[44:45], v[38:39], v[60:61] neg_lo:[0,0,1] neg_hi:[0,0,1]
	v_pk_fma_f32 v[38:39], v[44:45], v[38:39], v[60:61] op_sel_hi:[1,0,1]
	v_mov_b32_e32 v67, v41
	v_pk_mul_f32 v[42:43], v[46:47], v[64:65] op_sel:[1,0] op_sel_hi:[0,0]
	v_mov_b32_e32 v57, v33
	v_mov_b32_e32 v37, v39
	v_pk_mul_f32 v[38:39], v[48:49], v[66:67]
	v_pk_fma_f32 v[32:33], v[46:47], v[34:35], v[42:43] neg_lo:[0,0,1] neg_hi:[0,0,1]
	v_pk_fma_f32 v[34:35], v[46:47], v[62:63], v[42:43] op_sel_hi:[1,0,1]
	v_pk_mul_f32 v[40:41], v[50:51], v[56:57]
	v_sub_f32_e32 v31, v38, v39
	v_pk_mul_f32 v[36:37], v[52:53], v[36:37]
	v_mov_b32_e32 v33, v35
	v_sub_f32_e32 v34, v40, v41
	v_add_f32_e32 v6, v6, v31
	v_sub_f32_e32 v35, v36, v37
	v_pk_mul_f32 v[32:33], v[54:55], v[32:33]
	v_add_f32_e32 v6, v6, v34
	v_sub_f32_e32 v31, v32, v33
	v_add_f32_e32 v6, v6, v35
	v_add_f32_e32 v6, v6, v31
	s_waitcnt vmcnt(20)
	v_mov_b64_e32 v[32:33], v[116:117]
	v_mov_b64_e32 v[34:35], v[118:119]
	v_mov_b64_e32 v[36:37], v[120:121]
	v_mov_b64_e32 v[38:39], v[122:123]
	v_mov_b64_e32 v[48:49], v[124:125]
	v_mov_b64_e32 v[50:51], v[126:127]
	v_mov_b64_e32 v[52:53], v[128:129]
	v_mov_b64_e32 v[54:55], v[130:131]
	s_add_i32 s11, s10, 0
	v_mov_b32_e32 v31, s11
	ds_read_b128 v[40:43], v31
	ds_read_b128 v[44:47], v31 offset:16
	s_add_i32 s10, s10, 32
	s_waitcnt lgkmcnt(1)
	v_pk_mul_f32 v[56:57], v[40:41], v[32:33] op_sel:[1,0] op_sel_hi:[0,0]
	v_mov_b32_e32 v58, v37
	v_pk_mul_f32 v[32:33], v[42:43], v[32:33] op_sel:[1,1] op_sel_hi:[0,1]
	s_waitcnt lgkmcnt(0)
; __device__ __forceinline__ void phase0a(const int wvs, const Params& p, LAS unsigned char* lds) {
;     ...
;         for (int q = 0; q < 64; ++q) { const float tr = T[q * 2], ti = T[q * 2 + 1], xr = cre[q], xi = cim[q], yr = bre[q * 16], yi = bim[q * 16];
;           const float ur = xr * tr - xi * ti, ui = xr * ti + xi * tr; s += ur * yr - ui * yi; }
;         kd[(((size_t)(l * 2 + d) * 16 + g) * 16 + delta) * 256 + tid] = s; }
	v_pk_mul_f32 v[60:61], v[44:45], v[34:35] op_sel:[1,0] op_sel_hi:[0,0]
	v_pk_fma_f32 v[66:67], v[40:41], v[36:37], v[56:57] neg_lo:[0,0,1] neg_hi:[0,0,1]
	v_pk_fma_f32 v[40:41], v[40:41], v[36:37], v[56:57] op_sel_hi:[1,0,1]
	v_mov_b32_e32 v34, v39
	v_mov_b32_e32 v62, v39
	v_mov_b32_e32 v64, v35
	v_pk_fma_f32 v[56:57], v[42:43], v[58:59], v[32:33] neg_lo:[0,0,1] neg_hi:[0,0,1]
	v_pk_fma_f32 v[32:33], v[42:43], v[36:37], v[32:33] op_sel:[0,1,0]
	v_pk_fma_f32 v[36:37], v[44:45], v[38:39], v[60:61] neg_lo:[0,0,1] neg_hi:[0,0,1]
	v_pk_fma_f32 v[38:39], v[44:45], v[38:39], v[60:61] op_sel_hi:[1,0,1]
	v_mov_b32_e32 v67, v41
	v_pk_mul_f32 v[42:43], v[46:47], v[64:65] op_sel:[1,0] op_sel_hi:[0,0]
	v_mov_b32_e32 v57, v33
	v_mov_b32_e32 v37, v39
	v_pk_mul_f32 v[38:39], v[48:49], v[66:67]
	v_pk_fma_f32 v[32:33], v[46:47], v[34:35], v[42:43] neg_lo:[0,0,1] neg_hi:[0,0,1]
	v_pk_fma_f32 v[34:35], v[46:47], v[62:63], v[42:43] op_sel_hi:[1,0,1]
	v_pk_mul_f32 v[40:41], v[50:51], v[56:57]
	v_sub_f32_e32 v31, v38, v39
	v_pk_mul_f32 v[36:37], v[52:53], v[36:37]
	v_mov_b32_e32 v33, v35
	v_sub_f32_e32 v34, v40, v41
	v_add_f32_e32 v6, v6, v31
	v_sub_f32_e32 v35, v36, v37
	v_pk_mul_f32 v[32:33], v[54:55], v[32:33]
	v_add_f32_e32 v6, v6, v34
	v_sub_f32_e32 v31, v32, v33
	v_add_f32_e32 v6, v6, v35
	v_add_f32_e32 v6, v6, v31
	s_waitcnt vmcnt(10)
	v_mov_b64_e32 v[32:33], v[132:133]
	v_mov_b64_e32 v[34:35], v[134:135]
	v_mov_b64_e32 v[36:37], v[136:137]
	v_mov_b64_e32 v[38:39], v[138:139]
	v_mov_b64_e32 v[48:49], v[140:141]
	v_mov_b64_e32 v[50:51], v[142:143]
	v_mov_b64_e32 v[52:53], v[144:145]
	v_mov_b64_e32 v[54:55], v[146:147]
	s_add_i32 s11, s10, 0
	v_mov_b32_e32 v31, s11
	ds_read_b128 v[40:43], v31
	ds_read_b128 v[44:47], v31 offset:16
	s_add_i32 s10, s10, 32
	s_waitcnt lgkmcnt(1)
	v_pk_mul_f32 v[56:57], v[40:41], v[32:33] op_sel:[1,0] op_sel_hi:[0,0]
	v_mov_b32_e32 v58, v37
	v_pk_mul_f32 v[32:33], v[42:43], v[32:33] op_sel:[1,1] op_sel_hi:[0,1]
	s_waitcnt lgkmcnt(0)
	v_pk_mul_f32 v[60:61], v[44:45], v[34:35] op_sel:[1,0] op_sel_hi:[0,0]
	v_pk_fma_f32 v[66:67], v[40:41], v[36:37], v[56:57] neg_lo:[0,0,1] neg_hi:[0,0,1]
	v_pk_fma_f32 v[40:41], v[40:41], v[36:37], v[56:57] op_sel_hi:[1,0,1]
	v_mov_b32_e32 v34, v39
	v_mov_b32_e32 v62, v39
	v_mov_b32_e32 v64, v35
	v_pk_fma_f32 v[56:57], v[42:43], v[58:59], v[32:33] neg_lo:[0,0,1] neg_hi:[0,0,1]
	v_pk_fma_f32 v[32:33], v[42:43], v[36:37], v[32:33] op_sel:[0,1,0]
	v_pk_fma_f32 v[36:37], v[44:45], v[38:39], v[60:61] neg_lo:[0,0,1] neg_hi:[0,0,1]
	v_pk_fma_f32 v[38:39], v[44:45], v[38:39], v[60:61] op_sel_hi:[1,0,1]
	v_mov_b32_e32 v67, v41
	v_pk_mul_f32 v[42:43], v[46:47], v[64:65] op_sel:[1,0] op_sel_hi:[0,0]
	v_mov_b32_e32 v57, v33
	v_mov_b32_e32 v37, v39
	v_pk_mul_f32 v[38:39], v[48:49], v[66:67]
	v_pk_fma_f32 v[32:33], v[46:47], v[34:35], v[42:43] neg_lo:[0,0,1] neg_hi:[0,0,1]
	v_pk_fma_f32 v[34:35], v[46:47], v[62:63], v[42:43] op_sel_hi:[1,0,1]
	v_pk_mul_f32 v[40:41], v[50:51], v[56:57]
	v_sub_f32_e32 v31, v38, v39
	v_pk_mul_f32 v[36:37], v[52:53], v[36:37]
	v_mov_b32_e32 v33, v35
	v_sub_f32_e32 v34, v40, v41
	v_add_f32_e32 v6, v6, v31
	v_sub_f32_e32 v35, v36, v37
	v_pk_mul_f32 v[32:33], v[54:55], v[32:33]
	v_add_f32_e32 v6, v6, v34
	v_sub_f32_e32 v31, v32, v33
	v_add_f32_e32 v6, v6, v35
	v_add_f32_e32 v6, v6, v31
	s_waitcnt vmcnt(0)
	v_mov_b64_e32 v[32:33], v[148:149]
	v_mov_b64_e32 v[34:35], v[150:151]
	v_mov_b64_e32 v[36:37], v[152:153]
	v_mov_b64_e32 v[38:39], v[154:155]
	v_mov_b64_e32 v[48:49], v[156:157]
	v_mov_b64_e32 v[50:51], v[158:159]
	v_mov_b64_e32 v[52:53], v[160:161]
	v_mov_b64_e32 v[54:55], v[162:163]
	s_add_i32 s11, s10, 0
	v_mov_b32_e32 v31, s11
	ds_read_b128 v[40:43], v31
	ds_read_b128 v[44:47], v31 offset:16
	s_add_i32 s10, s10, 32
	s_waitcnt lgkmcnt(1)
	v_pk_mul_f32 v[56:57], v[40:41], v[32:33] op_sel:[1,0] op_sel_hi:[0,0]
	v_mov_b32_e32 v58, v37
	v_pk_mul_f32 v[32:33], v[42:43], v[32:33] op_sel:[1,1] op_sel_hi:[0,1]
	s_waitcnt lgkmcnt(0)
	v_pk_mul_f32 v[60:61], v[44:45], v[34:35] op_sel:[1,0] op_sel_hi:[0,0]
	v_pk_fma_f32 v[66:67], v[40:41], v[36:37], v[56:57] neg_lo:[0,0,1] neg_hi:[0,0,1]
	v_pk_fma_f32 v[40:41], v[40:41], v[36:37], v[56:57] op_sel_hi:[1,0,1]
	v_mov_b32_e32 v34, v39
	v_mov_b32_e32 v62, v39
	v_mov_b32_e32 v64, v35
	v_pk_fma_f32 v[56:57], v[42:43], v[58:59], v[32:33] neg_lo:[0,0,1] neg_hi:[0,0,1]
	v_pk_fma_f32 v[32:33], v[42:43], v[36:37], v[32:33] op_sel:[0,1,0]
	v_pk_fma_f32 v[36:37], v[44:45], v[38:39], v[60:61] neg_lo:[0,0,1] neg_hi:[0,0,1]
	v_pk_fma_f32 v[38:39], v[44:45], v[38:39], v[60:61] op_sel_hi:[1,0,1]
	v_mov_b32_e32 v67, v41
	v_pk_mul_f32 v[42:43], v[46:47], v[64:65] op_sel:[1,0] op_sel_hi:[0,0]
	v_mov_b32_e32 v57, v33
	v_mov_b32_e32 v37, v39
	v_pk_mul_f32 v[38:39], v[48:49], v[66:67]
	v_pk_fma_f32 v[32:33], v[46:47], v[34:35], v[42:43] neg_lo:[0,0,1] neg_hi:[0,0,1]
	v_pk_fma_f32 v[34:35], v[46:47], v[62:63], v[42:43] op_sel_hi:[1,0,1]
	v_pk_mul_f32 v[40:41], v[50:51], v[56:57]
	v_sub_f32_e32 v31, v38, v39
	v_pk_mul_f32 v[36:37], v[52:53], v[36:37]
	v_mov_b32_e32 v33, v35
	v_sub_f32_e32 v34, v40, v41
	v_add_f32_e32 v6, v6, v31
	v_sub_f32_e32 v35, v36, v37
	v_pk_mul_f32 v[32:33], v[54:55], v[32:33]
	v_add_f32_e32 v6, v6, v34
	v_sub_f32_e32 v31, v32, v33
	v_add_f32_e32 v6, v6, v35
	v_add_f32_e32 v6, v6, v31
	s_lshl_b32 s8, s25, 1
	s_add_i32 s8, s8, s23
	s_ashr_i32 s9, s8, 31
	s_ashr_i32 s25, s24, 31
	s_lshl_b64 s[8:9], s[8:9], 18
	s_ashr_i32 s23, s22, 31
	s_lshl_b64 s[10:11], s[24:25], 14
	v_lshl_add_u64 v[16:17], v[2:3], 0, s[8:9]
	s_lshl_b64 s[22:23], s[22:23], 10
	v_lshl_add_u64 v[16:17], v[16:17], 0, s[10:11]
	v_lshl_add_u64 v[16:17], v[16:17], 0, s[22:23]
	global_store_dword v[16:17], v6, off
	s_branch .LBB0_12
